# SGU: all 16 LayerNorm gain/bias loads issued together at the start of the normalize section (counted waits 12/8/4/0) instead of 4 serialized groups
# baseline (speedup 1.0000x reference)
.Lsgu_join:
	global_load_dwordx4 v[18:21], v35, s[40:41] offset:16
	global_load_dwordx4 v[22:25], v35, s[40:41]
	global_load_dwordx4 v[26:29], v35, s[46:47] offset:16
	global_load_dwordx4 v[30:33], v35, s[46:47]
	global_load_dwordx4 v[48:51], v35, s[40:41] offset:144
	global_load_dwordx4 v[52:55], v35, s[40:41] offset:128
	global_load_dwordx4 v[56:59], v35, s[46:47] offset:144
	global_load_dwordx4 v[60:63], v35, s[46:47] offset:128
	global_load_dwordx4 v[64:67], v35, s[40:41] offset:272
	global_load_dwordx4 v[68:71], v35, s[40:41] offset:256
	global_load_dwordx4 v[72:75], v35, s[46:47] offset:272
	global_load_dwordx4 v[76:79], v35, s[46:47] offset:256
	global_load_dwordx4 v[40:43], v35, s[40:41] offset:400
	global_load_dwordx4 v[80:83], v35, s[40:41] offset:384
	global_load_dwordx4 v[84:87], v35, s[46:47] offset:400
	global_load_dwordx4 v[88:91], v35, s[46:47] offset:384
	v_mul_f32_e32 v36, v36, v16
	v_mul_f32_e32 v12, v12, v16
	v_fmac_f32_e32 v15, 0xbb000000, v17
	v_or_b32_e32 v131, s36, v132
	v_or_b32_e32 v142, 16, v131
	v_or_b32_e32 v141, 32, v131
	v_or_b32_e32 v140, 48, v131
	v_or_b32_e32 v139, 64, v131
	v_or_b32_e32 v138, 0x50, v131
	v_or_b32_e32 v137, 0x60, v131
	v_or_b32_e32 v133, 0x70, v131
	s_waitcnt vmcnt(12)
	v_fma_f32 v22, v22, v36, v30
	v_mul_u32_u24_e32 v30, 0x110, v45
	v_fma_f32 v12, v23, v12, v31
	v_add3_u32 v30, 0, v34, v30
	v_cvt_pk_bf16_f32 v12, v12, s0
	ds_write_b16 v30, v12 offset:272
	v_mul_f32_e32 v12, v37, v16
	v_fma_f32 v12, v24, v12, v32
	v_cvt_pk_bf16_f32 v12, v12, s0
	ds_write_b16 v30, v12 offset:544
	v_mul_f32_e32 v12, v13, v16
	v_fmac_f32_e32 v33, v25, v12
	v_cvt_pk_bf16_f32 v12, v33, s0
	ds_write_b16 v30, v12 offset:816
	v_mul_f32_e32 v12, v38, v16
	v_fma_f32 v12, v18, v12, v26
	v_cvt_pk_bf16_f32 v12, v12, s0
	ds_write_b16 v30, v12 offset:1088
	v_mul_f32_e32 v12, v14, v16
	v_fma_f32 v12, v19, v12, v27
	v_cvt_pk_bf16_f32 v12, v12, s0
	ds_write_b16 v30, v12 offset:1360
	v_mul_f32_e32 v12, v39, v16
	v_fma_f32 v12, v20, v12, v28
	v_cvt_pk_bf16_f32 v12, v12, s0
	ds_write_b16 v30, v12 offset:1632
	v_mul_f32_e32 v12, v15, v16
	v_fmac_f32_e32 v29, v21, v12
	v_cvt_pk_bf16_f32 v22, v22, s0
	v_cvt_pk_bf16_f32 v12, v29, s0
	ds_write_b16 v30, v22
	ds_write_b16 v30, v12 offset:1904
	v_lshlrev_b32_e32 v31, 16, v8
	v_and_b32_e32 v8, 0xffff0000, v8
	v_fmac_f32_e32 v8, 0xbb000000, v17
	v_mul_f32_e32 v8, v8, v16
	v_lshlrev_b32_e32 v32, 16, v9
	v_fmac_f32_e32 v32, 0xbb000000, v17
	v_and_b32_e32 v9, 0xffff0000, v9
	v_fmac_f32_e32 v9, 0xbb000000, v17
	v_lshlrev_b32_e32 v33, 16, v10
	v_fmac_f32_e32 v33, 0xbb000000, v17
	v_and_b32_e32 v10, 0xffff0000, v10
	v_fmac_f32_e32 v10, 0xbb000000, v17
	v_lshlrev_b32_e32 v34, 16, v11
	v_fmac_f32_e32 v34, 0xbb000000, v17
	v_and_b32_e32 v11, 0xffff0000, v11
	v_fmac_f32_e32 v31, 0xbb000000, v17
	v_fmac_f32_e32 v11, 0xbb000000, v17
	v_mul_f32_e32 v31, v31, v16
	s_waitcnt vmcnt(8)
	v_fma_f32 v8, v53, v8, v61
	v_cvt_pk_bf16_f32 v8, v8, s0
	ds_write_b16 v30, v8 offset:8976
	v_mul_f32_e32 v8, v32, v16
	v_fma_f32 v8, v54, v8, v62
	v_cvt_pk_bf16_f32 v8, v8, s0
	ds_write_b16 v30, v8 offset:9248
	v_mul_f32_e32 v8, v9, v16
	v_fmac_f32_e32 v63, v55, v8
	v_cvt_pk_bf16_f32 v8, v63, s0
	ds_write_b16 v30, v8 offset:9520
	v_mul_f32_e32 v8, v33, v16
	v_fma_f32 v8, v48, v8, v56
	v_cvt_pk_bf16_f32 v8, v8, s0
	ds_write_b16 v30, v8 offset:9792
	v_mul_f32_e32 v8, v10, v16
	v_fma_f32 v8, v49, v8, v57
	v_cvt_pk_bf16_f32 v8, v8, s0
	ds_write_b16 v30, v8 offset:10064
	v_mul_f32_e32 v8, v34, v16
	v_fma_f32 v8, v50, v8, v58
	v_cvt_pk_bf16_f32 v8, v8, s0
	ds_write_b16 v30, v8 offset:10336
	v_mul_f32_e32 v8, v11, v16
	v_fma_f32 v18, v52, v31, v60
	v_fmac_f32_e32 v59, v51, v8
	v_cvt_pk_bf16_f32 v18, v18, s0
	v_cvt_pk_bf16_f32 v8, v59, s0
	ds_write_b16 v30, v18 offset:8704
	ds_write_b16 v30, v8 offset:10608
	v_lshlrev_b32_e32 v26, 16, v4
	v_and_b32_e32 v4, 0xffff0000, v4
	v_fmac_f32_e32 v4, 0xbb000000, v17
	v_mul_f32_e32 v4, v4, v16
	v_lshlrev_b32_e32 v27, 16, v5
	v_fmac_f32_e32 v27, 0xbb000000, v17
	v_and_b32_e32 v5, 0xffff0000, v5
	v_fmac_f32_e32 v5, 0xbb000000, v17
	v_lshlrev_b32_e32 v28, 16, v6
	v_fmac_f32_e32 v28, 0xbb000000, v17
	v_and_b32_e32 v6, 0xffff0000, v6
	v_fmac_f32_e32 v6, 0xbb000000, v17
	v_lshlrev_b32_e32 v29, 16, v7
	v_fmac_f32_e32 v29, 0xbb000000, v17
	v_and_b32_e32 v7, 0xffff0000, v7
	v_fmac_f32_e32 v26, 0xbb000000, v17
	v_fmac_f32_e32 v7, 0xbb000000, v17
	v_mul_f32_e32 v26, v26, v16
	s_waitcnt vmcnt(4)
	v_fma_f32 v4, v69, v4, v77
	v_cvt_pk_bf16_f32 v4, v4, s0
	ds_write_b16 v30, v4 offset:17680
	v_mul_f32_e32 v4, v27, v16
	v_fma_f32 v4, v70, v4, v78
	v_cvt_pk_bf16_f32 v4, v4, s0
	ds_write_b16 v30, v4 offset:17952
	v_mul_f32_e32 v4, v5, v16
	v_fmac_f32_e32 v79, v71, v4
	v_cvt_pk_bf16_f32 v4, v79, s0
	ds_write_b16 v30, v4 offset:18224
	v_mul_f32_e32 v4, v28, v16
	v_fma_f32 v4, v64, v4, v72
	v_cvt_pk_bf16_f32 v4, v4, s0
	ds_write_b16 v30, v4 offset:18496
	v_mul_f32_e32 v4, v6, v16
	v_fma_f32 v4, v65, v4, v73
	v_cvt_pk_bf16_f32 v4, v4, s0
	ds_write_b16 v30, v4 offset:18768
	v_mul_f32_e32 v4, v29, v16
	v_fma_f32 v4, v66, v4, v74
	v_cvt_pk_bf16_f32 v4, v4, s0
	ds_write_b16 v30, v4 offset:19040
	v_mul_f32_e32 v4, v7, v16
	v_fma_f32 v12, v68, v26, v76
	v_fmac_f32_e32 v75, v67, v4
	v_cvt_pk_bf16_f32 v12, v12, s0
	v_cvt_pk_bf16_f32 v4, v75, s0
	ds_write_b16 v30, v12 offset:17408
	ds_write_b16 v30, v4 offset:19312
	v_lshlrev_b32_e32 v22, 16, v0
	v_and_b32_e32 v0, 0xffff0000, v0
	v_fmac_f32_e32 v0, 0xbb000000, v17
	v_mul_f32_e32 v0, v0, v16
	v_lshlrev_b32_e32 v23, 16, v1
	v_fmac_f32_e32 v23, 0xbb000000, v17
	v_and_b32_e32 v1, 0xffff0000, v1
	v_fmac_f32_e32 v1, 0xbb000000, v17
	v_lshlrev_b32_e32 v24, 16, v2
	v_fmac_f32_e32 v24, 0xbb000000, v17
	v_and_b32_e32 v2, 0xffff0000, v2
	v_fmac_f32_e32 v2, 0xbb000000, v17
	v_lshlrev_b32_e32 v25, 16, v3
	v_fmac_f32_e32 v25, 0xbb000000, v17
	v_and_b32_e32 v3, 0xffff0000, v3
	v_fmac_f32_e32 v3, 0xbb000000, v17
	v_fmac_f32_e32 v22, 0xbb000000, v17
	v_mul_f32_e32 v22, v22, v16
	v_and_b32_e32 v17, -16, v130
	s_waitcnt vmcnt(0)
	v_fma_f32 v0, v81, v0, v89
	v_cvt_pk_bf16_f32 v0, v0, s0
	ds_write_b16 v30, v0 offset:26384
	v_mul_f32_e32 v0, v23, v16
	v_fma_f32 v0, v82, v0, v90
	v_cvt_pk_bf16_f32 v0, v0, s0
	ds_write_b16 v30, v0 offset:26656
	v_mul_f32_e32 v0, v1, v16
	v_fmac_f32_e32 v91, v83, v0
	v_cvt_pk_bf16_f32 v0, v91, s0
	ds_write_b16 v30, v0 offset:26928
	v_mul_f32_e32 v0, v24, v16
	v_fma_f32 v0, v40, v0, v84
	v_cvt_pk_bf16_f32 v0, v0, s0
	ds_write_b16 v30, v0 offset:27200
	v_mul_f32_e32 v0, v2, v16
	v_fma_f32 v0, v41, v0, v85
	v_cvt_pk_bf16_f32 v0, v0, s0
	ds_write_b16 v30, v0 offset:27472
	v_mul_f32_e32 v0, v25, v16
	v_fma_f32 v0, v42, v0, v86
	v_cvt_pk_bf16_f32 v0, v0, s0
	ds_write_b16 v30, v0 offset:27744
	v_mul_f32_e32 v0, v3, v16
	v_ashrrev_i32_e32 v4, 4, v130
	v_fmac_f32_e32 v87, v43, v0
	v_lshlrev_b32_e32 v92, 2, v4
	v_cvt_pk_bf16_f32 v0, v87, s0
	v_ashrrev_i32_e32 v93, 31, v92
	ds_write_b16 v30, v0 offset:28016
	v_lshl_add_u64 v[0:1], v[92:93], 1, s[8:9]
	v_mad_u64_u32 v[2:3], s[8:9], v131, s14, v[0:1]
	v_mad_i32_i24 v3, s37, v225, v3
	global_load_dwordx2 v[126:127], v[2:3], off offset:1024
	v_add_co_u32_e32 v2, vcc, s15, v2
	v_fma_f32 v8, v80, v22, v88
	s_nop 0
	v_addc_co_u32_e32 v3, vcc, 0, v3, vcc
	global_load_dwordx2 v[128:129], v[2:3], off offset:2048
	v_mad_u64_u32 v[2:3], s[8:9], v142, s14, v[0:1]
	v_mad_i32_i24 v3, s37, v225, v3
	global_load_dwordx2 v[122:123], v[2:3], off offset:1024
	v_add_co_u32_e32 v2, vcc, s15, v2
	v_cvt_pk_bf16_f32 v8, v8, s0
	s_nop 0
	v_addc_co_u32_e32 v3, vcc, 0, v3, vcc
	global_load_dwordx2 v[124:125], v[2:3], off offset:2048
	v_mad_u64_u32 v[2:3], s[8:9], v141, s14, v[0:1]
	v_mad_i32_i24 v3, s37, v225, v3
	global_load_dwordx2 v[118:119], v[2:3], off offset:1024
	v_add_co_u32_e32 v2, vcc, s15, v2
	ds_write_b16 v30, v8 offset:26112
	s_nop 0
	v_addc_co_u32_e32 v3, vcc, 0, v3, vcc
	global_load_dwordx2 v[120:121], v[2:3], off offset:2048
	v_mad_u64_u32 v[2:3], s[8:9], v140, s14, v[0:1]
	v_mad_i32_i24 v3, s37, v225, v3
	global_load_dwordx2 v[114:115], v[2:3], off offset:1024
	v_add_co_u32_e32 v2, vcc, s15, v2
	v_or_b32_e32 v16, s10, v132
	s_nop 0
	v_addc_co_u32_e32 v3, vcc, 0, v3, vcc
	global_load_dwordx2 v[116:117], v[2:3], off offset:2048
	v_mad_u64_u32 v[2:3], s[8:9], v139, s14, v[0:1]
	v_mad_i32_i24 v3, s37, v225, v3
	global_load_dwordx2 v[110:111], v[2:3], off offset:1024
	v_add_co_u32_e32 v2, vcc, s15, v2
	v_or_b32_e32 v132, s60, v132
	s_nop 0
	v_addc_co_u32_e32 v3, vcc, 0, v3, vcc
	global_load_dwordx2 v[112:113], v[2:3], off offset:2048
	v_mad_u64_u32 v[2:3], s[8:9], v138, s14, v[0:1]
	v_mad_i32_i24 v3, s37, v225, v3
	global_load_dwordx2 v[106:107], v[2:3], off offset:1024
	v_add_co_u32_e32 v2, vcc, s15, v2
	v_lshlrev_b32_e32 v136, 2, v132
	s_nop 0
	v_addc_co_u32_e32 v3, vcc, 0, v3, vcc
	global_load_dwordx2 v[108:109], v[2:3], off offset:2048
	v_mad_u64_u32 v[2:3], s[8:9], v137, s14, v[0:1]
	v_mad_u64_u32 v[0:1], s[8:9], v133, s14, v[0:1]
	v_mad_i32_i24 v3, s37, v225, v3
	v_mad_i32_i24 v1, s37, v225, v1
	global_load_dwordx2 v[100:101], v[2:3], off offset:1024
	global_load_dwordx2 v[96:97], v[0:1], off offset:1024
	v_add_co_u32_e32 v2, vcc, s15, v2
	s_add_u32 s8, s3, s7
	s_nop 0
	v_addc_co_u32_e32 v3, vcc, 0, v3, vcc
	v_add_co_u32_e32 v0, vcc, s15, v0
	s_addc_u32 s9, s11, 0
	s_nop 0
	v_addc_co_u32_e32 v1, vcc, 0, v1, vcc
	global_load_dwordx2 v[98:99], v[0:1], off offset:2048
	v_lshlrev_b32_e32 v0, 3, v4
	v_ashrrev_i32_e32 v1, 31, v0
	v_lshl_add_u64 v[0:1], v[0:1], 1, s[8:9]
	v_lshl_add_u64 v[0:1], v[0:1], 0, v[194:195]
	global_load_dwordx2 v[104:105], v[2:3], off offset:2048
	global_load_dwordx4 v[144:147], v[0:1], off
	v_add_co_u32_e32 v2, vcc, s4, v0
	s_movk_i32 s7, 0x4000
	s_nop 0
	v_addc_co_u32_e32 v3, vcc, 0, v1, vcc
	global_load_dwordx4 v[88:91], v[2:3], off offset:-4096
	global_load_dwordx4 v[80:83], v[2:3], off
	global_load_dwordx4 v[84:87], v[2:3], off offset:64
	v_add_co_u32_e32 v2, vcc, s35, v0
	s_waitcnt vmcnt(18)
	v_lshlrev_b32_e32 v143, 16, v128
	v_addc_co_u32_e32 v3, vcc, 0, v1, vcc
	v_add_co_u32_e32 v4, vcc, s7, v0
	s_movk_i32 s7, 0x5000
	s_nop 0
	v_addc_co_u32_e32 v5, vcc, 0, v1, vcc
	global_load_dwordx4 v[72:75], v[4:5], off offset:-4096
	global_load_dwordx4 v[76:79], v[2:3], off offset:64
	global_load_dwordx4 v[60:63], v[4:5], off
	global_load_dwordx4 v[64:67], v[4:5], off offset:64
	global_load_dwordx4 v[68:71], v[4:5], off offset:128
	v_add_co_u32_e32 v2, vcc, s7, v0
	s_movk_i32 s7, 0x7000
	s_nop 0
	v_addc_co_u32_e32 v3, vcc, 0, v1, vcc
	v_add_co_u32_e32 v4, vcc, s95, v0
	v_and_b32_e32 v128, 0xffff0000, v128
	s_nop 0
	v_addc_co_u32_e32 v5, vcc, 0, v1, vcc
	v_add_co_u32_e32 v12, vcc, s7, v0
	s_movk_i32 s7, 0x110
	v_mul_lo_u32 v16, v16, s7
	v_addc_co_u32_e32 v13, vcc, 0, v1, vcc
	v_add3_u32 v28, 0, v16, v17
	global_load_dwordx4 v[48:51], v[4:5], off offset:-4096
	global_load_dwordx4 v[52:55], v[2:3], off offset:64
	global_load_dwordx4 v[56:59], v[2:3], off offset:128
	global_load_dwordx4 v[32:35], v[4:5], off
	global_load_dwordx4 v[36:39], v[4:5], off offset:64
	global_load_dwordx4 v[40:43], v[4:5], off offset:128
	global_load_dwordx4 v[44:47], v[4:5], off offset:192
	s_nop 0
	global_load_dwordx4 v[0:3], v[12:13], off
	global_load_dwordx4 v[4:7], v[12:13], off offset:64
	global_load_dwordx4 v[8:11], v[12:13], off offset:128
	s_nop 0
	global_load_dwordx4 v[12:15], v[12:13], off offset:192
	s_waitcnt lgkmcnt(0)
	s_barrier
	ds_read_b128 v[16:19], v28
	ds_read_b128 v[20:23], v28 offset:64
	ds_read_b128 v[24:27], v28 offset:128
	ds_read_b128 v[28:31], v28 offset:192
	global_load_dword v132, v136, s[0:1]
	global_load_dword v160, v136, s[0:1] offset:64
	global_load_dword v162, v136, s[0:1] offset:128
	global_load_dword v164, v136, s[0:1] offset:192
	global_load_dword v166, v136, s[0:1] offset:256
	global_load_dword v168, v136, s[0:1] offset:320
	global_load_dword v170, v136, s[0:1] offset:384
	global_load_dword v172, v136, s[0:1] offset:448
	s_add_i32 s7, s60, s10
	v_add_u32_e32 v92, s7, v92
	v_ashrrev_i32_e32 v93, 31, v92
	v_lshl_add_u64 v[102:103], v[92:93], 1, s[82:83]
	s_waitcnt vmcnt(27) lgkmcnt(3)
	v_mfma_f32_16x16x32_bf16 v[92:95], v[16:19], v[144:147], 0
	v_mul_f32_e32 v134, 0xbfb8aa3b, v143
	v_lshlrev_b32_e32 v144, 16, v126
	v_and_b32_e32 v145, 0xffff0000, v126
	v_mul_f32_e32 v126, 0xbfb8aa3b, v128
	v_exp_f32_e32 v134, v134
	v_exp_f32_e32 v135, v126
	v_mad_u64_u32 v[130:131], s[8:9], v131, s14, v[102:103]
	v_mad_i32_i24 v131, s37, v225, v131
	v_pk_add_f32 v[134:135], v[134:135], 1.0 op_sel_hi:[1,0]
	s_waitcnt vmcnt(26)
	v_mfma_f32_16x16x32_bf16 v[88:91], v[16:19], v[88:91], 0
	s_add_i32 s65, s65, s98
	s_waitcnt vmcnt(25)
	v_mfma_f32_16x16x32_bf16 v[80:83], v[16:19], v[80:83], 0
	s_add_i32 s64, s64, s99
	s_cmp_gt_i32 s65, s88
	s_waitcnt vmcnt(0)
	v_pk_add_f32 v[92:93], v[92:93], v[132:133] op_sel_hi:[1,0]
	s_nop 0
	v_pk_mul_f32 v[92:93], v[92:93], v[144:145]
	v_rcp_f32_e32 v144, v135
	v_pk_add_f32 v[94:95], v[94:95], v[132:133] op_sel_hi:[1,0]
	s_waitcnt lgkmcnt(2)
	v_mfma_f32_16x16x32_bf16 v[80:83], v[20:23], v[84:87], v[80:83]
	v_lshlrev_b32_e32 v87, 16, v120
	v_mul_f32_e32 v135, v128, v144
	v_rcp_f32_e32 v128, v134
	v_mfma_f32_16x16x32_bf16 v[72:75], v[16:19], v[72:75], 0
	v_mad_u64_u32 v[84:85], s[8:9], v141, s14, v[102:103]
	v_mul_f32_e32 v134, v143, v128
	v_pk_mul_f32 v[92:93], v[134:135], v[92:93]
	v_lshlrev_b32_e32 v134, 16, v129
	v_and_b32_e32 v135, 0xffff0000, v129
	v_mul_f32_e32 v126, 0xbfb8aa3b, v134
	v_lshlrev_b32_e32 v128, 16, v127
	v_and_b32_e32 v129, 0xffff0000, v127
	v_mul_f32_e32 v127, 0xbfb8aa3b, v135
	v_exp_f32_e32 v126, v126
	v_exp_f32_e32 v127, v127
	v_pk_mul_f32 v[94:95], v[94:95], v[128:129]
	v_cvt_pk_bf16_f32 v92, v92, v93
	v_mad_i32_i24 v85, s37, v225, v85
	v_pk_add_f32 v[126:127], v[126:127], 1.0 op_sel_hi:[1,0]
	v_mfma_f32_16x16x32_bf16 v[72:75], v[20:23], v[76:79], v[72:75]
	v_rcp_f32_e32 v129, v127
	v_lshlrev_b32_e32 v79, 16, v116
	v_mfma_f32_16x16x32_bf16 v[60:63], v[16:19], v[60:63], 0
	v_mad_u64_u32 v[76:77], s[8:9], v140, s14, v[102:103]
	v_mul_f32_e32 v127, v135, v129
	v_rcp_f32_e32 v129, v126
	v_mad_i32_i24 v77, s37, v225, v77
	v_mfma_f32_16x16x32_bf16 v[60:63], v[20:23], v[64:67], v[60:63]
	v_lshlrev_b32_e32 v67, 16, v112
	v_mul_f32_e32 v126, v134, v129
	v_pk_mul_f32 v[94:95], v[126:127], v[94:95]
	v_lshlrev_b32_e32 v128, 16, v122
	v_cvt_pk_bf16_f32 v93, v94, v95
	global_store_dwordx2 v[130:131], v[92:93], off offset:1024
	v_lshlrev_b32_e32 v95, 16, v124
	v_and_b32_e32 v124, 0xffff0000, v124
	v_mul_f32_e32 v126, 0xbfb8aa3b, v95
	v_and_b32_e32 v129, 0xffff0000, v122
	v_mul_f32_e32 v122, 0xbfb8aa3b, v124
	v_exp_f32_e32 v126, v126
	v_exp_f32_e32 v127, v122
	v_mad_u64_u32 v[92:93], s[8:9], v142, s14, v[102:103]
	v_mad_i32_i24 v93, s37, v225, v93
	v_pk_add_f32 v[126:127], v[126:127], 1.0 op_sel_hi:[1,0]
	s_waitcnt lgkmcnt(1)
	v_mfma_f32_16x16x32_bf16 v[60:63], v[24:27], v[68:71], v[60:63]
	v_mul_f32_e32 v68, 0xbfb8aa3b, v67
	v_exp_f32_e32 v68, v68
	v_lshlrev_b32_e32 v70, 16, v110
	v_and_b32_e32 v71, 0xffff0000, v110
	v_mfma_f32_16x16x32_bf16 v[48:51], v[16:19], v[48:51], 0
	v_mad_u64_u32 v[64:65], s[8:9], v139, s14, v[102:103]
	v_mad_i32_i24 v65, s37, v225, v65
	v_mfma_f32_16x16x32_bf16 v[48:51], v[20:23], v[52:55], v[48:51]
	v_lshlrev_b32_e32 v55, 16, v108
	v_mad_u64_u32 v[52:53], s[8:9], v138, s14, v[102:103]
	v_mfma_f32_16x16x32_bf16 v[48:51], v[24:27], v[56:59], v[48:51]
	v_mul_f32_e32 v56, 0xbfb8aa3b, v55
	v_exp_f32_e32 v56, v56
	v_lshlrev_b32_e32 v58, 16, v106
	v_and_b32_e32 v59, 0xffff0000, v106
	v_mfma_f32_16x16x32_bf16 v[32:35], v[16:19], v[32:35], 0
	v_mad_i32_i24 v53, s37, v225, v53
	v_pk_add_f32 v[88:89], v[88:89], v[160:161] op_sel_hi:[1,0]
	s_nop 0
	v_pk_mul_f32 v[88:89], v[88:89], v[128:129]
	v_rcp_f32_e32 v128, v127
	v_mfma_f32_16x16x32_bf16 v[32:35], v[20:23], v[36:39], v[32:35]
	v_lshlrev_b32_e32 v39, 16, v104
	v_mad_u64_u32 v[36:37], s[8:9], v137, s14, v[102:103]
	v_mul_f32_e32 v127, v124, v128
	v_rcp_f32_e32 v124, v126
	v_mfma_f32_16x16x32_bf16 v[32:35], v[24:27], v[40:43], v[32:35]
	v_mul_f32_e32 v40, 0xbfb8aa3b, v39
	v_exp_f32_e32 v40, v40
	v_mul_f32_e32 v126, v95, v124
	v_pk_mul_f32 v[88:89], v[126:127], v[88:89]
	v_lshlrev_b32_e32 v126, 16, v125
	v_and_b32_e32 v127, 0xffff0000, v125
	v_mul_f32_e32 v95, 0xbfb8aa3b, v126
	v_pk_add_f32 v[90:91], v[90:91], v[160:161] op_sel_hi:[1,0]
	v_mul_f32_e32 v94, 0xbfb8aa3b, v127
	v_exp_f32_e32 v122, v95
	v_lshlrev_b32_e32 v124, 16, v123
	v_and_b32_e32 v125, 0xffff0000, v123
	v_exp_f32_e32 v123, v94
	v_pk_mul_f32 v[90:91], v[90:91], v[124:125]
	v_cvt_pk_bf16_f32 v88, v88, v89
	s_waitcnt lgkmcnt(0)
	v_mfma_f32_16x16x32_bf16 v[32:35], v[28:31], v[44:47], v[32:35]
	v_add_f32_e64 v94, v122, 1.0
	v_add_f32_e64 v95, v123, 1.0
	v_and_b32_e32 v44, 0xffff0000, v104
	v_rcp_f32_e32 v123, v95
	v_mul_f32_e32 v41, 0xbfb8aa3b, v44
	v_exp_f32_e32 v41, v41
	v_lshlrev_b32_e32 v42, 16, v100
	v_mul_f32_e32 v95, v127, v123
	v_rcp_f32_e32 v123, v94
	v_and_b32_e32 v43, 0xffff0000, v100
	v_pk_add_f32 v[40:41], v[40:41], 1.0 op_sel_hi:[1,0]
	v_mfma_f32_16x16x32_bf16 v[0:3], v[16:19], v[0:3], 0
	v_mul_f32_e32 v122, v126, v123
	v_mov_b32_e32 v94, v122
	v_pk_mul_f32 v[90:91], v[94:95], v[90:91]
	v_mad_i32_i24 v37, s37, v225, v37
	v_cvt_pk_bf16_f32 v89, v90, v91
	global_store_dwordx2 v[92:93], v[88:89], off offset:1024
	v_and_b32_e32 v92, 0xffff0000, v120
	v_mul_f32_e32 v88, 0xbfb8aa3b, v87
	v_mul_f32_e32 v89, 0xbfb8aa3b, v92
	v_exp_f32_e32 v88, v88
	v_exp_f32_e32 v89, v89
	v_lshlrev_b32_e32 v90, 16, v118
	v_and_b32_e32 v91, 0xffff0000, v118
	v_mfma_f32_16x16x32_bf16 v[0:3], v[20:23], v[4:7], v[0:3]
	v_add_f32_e64 v88, v88, 1.0
	v_add_f32_e64 v89, v89, 1.0
	v_lshlrev_b32_e32 v7, 16, v98
	v_mad_u64_u32 v[4:5], s[8:9], v133, s14, v[102:103]
	v_mfma_f32_16x16x32_bf16 v[0:3], v[24:27], v[8:11], v[0:3]
	v_mul_f32_e32 v8, 0xbfb8aa3b, v7
	v_exp_f32_e32 v8, v8
	v_lshlrev_b32_e32 v10, 16, v96
	v_mfma_f32_16x16x32_bf16 v[0:3], v[28:31], v[12:15], v[0:3]
	v_and_b32_e32 v12, 0xffff0000, v98
	v_mul_f32_e32 v9, 0xbfb8aa3b, v12
	v_exp_f32_e32 v9, v9
	v_and_b32_e32 v11, 0xffff0000, v96
	v_mad_i32_i24 v5, s37, v225, v5
	v_pk_add_f32 v[8:9], v[8:9], 1.0 op_sel_hi:[1,0]
	v_pk_add_f32 v[80:81], v[80:81], v[162:163] op_sel_hi:[1,0]
	s_nop 0
	v_pk_mul_f32 v[80:81], v[80:81], v[90:91]
	v_rcp_f32_e32 v91, v89
	s_nop 0
	v_mul_f32_e32 v89, v92, v91
	v_rcp_f32_e32 v91, v88
	s_nop 0
	v_mul_f32_e32 v90, v87, v91
	v_lshlrev_b32_e32 v92, 16, v121
	v_mov_b32_e32 v88, v90
	v_and_b32_e32 v93, 0xffff0000, v121
	v_mul_f32_e32 v87, 0xbfb8aa3b, v92
	v_pk_add_f32 v[82:83], v[82:83], v[162:163] op_sel_hi:[1,0]
	v_mul_f32_e32 v86, 0xbfb8aa3b, v93
	v_pk_mul_f32 v[80:81], v[88:89], v[80:81]
	v_exp_f32_e32 v88, v87
	v_exp_f32_e32 v89, v86
	v_lshlrev_b32_e32 v90, 16, v119
	v_and_b32_e32 v91, 0xffff0000, v119
	v_pk_mul_f32 v[82:83], v[82:83], v[90:91]
	v_pk_add_f32 v[86:87], v[88:89], 1.0 op_sel_hi:[1,0]
	v_cvt_pk_bf16_f32 v80, v80, v81
	v_rcp_f32_e32 v89, v87
	s_nop 0
	v_mul_f32_e32 v87, v93, v89
	v_rcp_f32_e32 v89, v86
	s_nop 0
	v_mul_f32_e32 v88, v92, v89
	v_mov_b32_e32 v86, v88
	v_pk_mul_f32 v[82:83], v[86:87], v[82:83]
	s_nop 0
	v_cvt_pk_bf16_f32 v81, v82, v83
	global_store_dwordx2 v[84:85], v[80:81], off offset:1024
	v_and_b32_e32 v84, 0xffff0000, v116
	v_mul_f32_e32 v80, 0xbfb8aa3b, v79
	v_mul_f32_e32 v81, 0xbfb8aa3b, v84
	v_exp_f32_e32 v80, v80
	v_exp_f32_e32 v81, v81
	v_lshlrev_b32_e32 v82, 16, v114
	v_and_b32_e32 v83, 0xffff0000, v114
	v_pk_add_f32 v[80:81], v[80:81], 1.0 op_sel_hi:[1,0]
	v_pk_add_f32 v[72:73], v[72:73], v[164:165] op_sel_hi:[1,0]
	s_nop 0
	v_pk_mul_f32 v[72:73], v[72:73], v[82:83]
	v_rcp_f32_e32 v83, v81
	s_nop 0
	v_mul_f32_e32 v81, v84, v83
	v_rcp_f32_e32 v83, v80
	s_nop 0
	v_mul_f32_e32 v82, v79, v83
	v_lshlrev_b32_e32 v84, 16, v117
	v_mov_b32_e32 v80, v82
	v_and_b32_e32 v85, 0xffff0000, v117
	v_mul_f32_e32 v79, 0xbfb8aa3b, v84
	v_pk_add_f32 v[74:75], v[74:75], v[164:165] op_sel_hi:[1,0]
	v_mul_f32_e32 v78, 0xbfb8aa3b, v85
	v_pk_mul_f32 v[72:73], v[80:81], v[72:73]
	v_exp_f32_e32 v80, v79
	v_exp_f32_e32 v81, v78
	v_lshlrev_b32_e32 v82, 16, v115
	v_and_b32_e32 v83, 0xffff0000, v115
	v_pk_mul_f32 v[74:75], v[74:75], v[82:83]
	v_pk_add_f32 v[78:79], v[80:81], 1.0 op_sel_hi:[1,0]
	v_cvt_pk_bf16_f32 v72, v72, v73
	v_rcp_f32_e32 v81, v79
	s_nop 0
	v_mul_f32_e32 v79, v85, v81
	v_rcp_f32_e32 v81, v78
	s_nop 0
	v_mul_f32_e32 v80, v84, v81
	v_mov_b32_e32 v78, v80
	v_pk_mul_f32 v[74:75], v[78:79], v[74:75]
	s_nop 0
	v_cvt_pk_bf16_f32 v73, v74, v75
	global_store_dwordx2 v[76:77], v[72:73], off offset:1024
	v_and_b32_e32 v72, 0xffff0000, v112
	v_mul_f32_e32 v69, 0xbfb8aa3b, v72
	v_exp_f32_e32 v69, v69
	v_pk_add_f32 v[60:61], v[60:61], v[166:167] op_sel_hi:[1,0]
	v_pk_add_f32 v[68:69], v[68:69], 1.0 op_sel_hi:[1,0]
	v_pk_mul_f32 v[60:61], v[60:61], v[70:71]
	v_rcp_f32_e32 v71, v69
	s_nop 0
	v_mul_f32_e32 v69, v72, v71
	v_rcp_f32_e32 v71, v68
	s_nop 0
	v_mul_f32_e32 v70, v67, v71
	v_lshlrev_b32_e32 v72, 16, v113
	v_mov_b32_e32 v68, v70
	v_and_b32_e32 v73, 0xffff0000, v113
	v_mul_f32_e32 v67, 0xbfb8aa3b, v72
	v_pk_add_f32 v[62:63], v[62:63], v[166:167] op_sel_hi:[1,0]
	v_mul_f32_e32 v66, 0xbfb8aa3b, v73
	v_pk_mul_f32 v[60:61], v[68:69], v[60:61]
	v_exp_f32_e32 v68, v67
	v_exp_f32_e32 v69, v66
	v_lshlrev_b32_e32 v70, 16, v111
	v_and_b32_e32 v71, 0xffff0000, v111
	v_pk_mul_f32 v[62:63], v[62:63], v[70:71]
	v_pk_add_f32 v[66:67], v[68:69], 1.0 op_sel_hi:[1,0]
	v_cvt_pk_bf16_f32 v60, v60, v61
	v_rcp_f32_e32 v69, v67
	s_nop 0
	v_mul_f32_e32 v67, v73, v69
	v_rcp_f32_e32 v69, v66
	s_nop 0
	v_mul_f32_e32 v68, v72, v69
	v_mov_b32_e32 v66, v68
	v_pk_mul_f32 v[62:63], v[66:67], v[62:63]
	s_nop 0
	v_cvt_pk_bf16_f32 v61, v62, v63
	global_store_dwordx2 v[64:65], v[60:61], off offset:1024
	v_and_b32_e32 v60, 0xffff0000, v108
	v_mul_f32_e32 v57, 0xbfb8aa3b, v60
	v_exp_f32_e32 v57, v57
	v_pk_add_f32 v[48:49], v[48:49], v[168:169] op_sel_hi:[1,0]
	v_pk_add_f32 v[56:57], v[56:57], 1.0 op_sel_hi:[1,0]
	v_pk_mul_f32 v[48:49], v[48:49], v[58:59]
	v_rcp_f32_e32 v59, v57
	s_nop 0
	v_mul_f32_e32 v57, v60, v59
	v_rcp_f32_e32 v59, v56
	s_nop 0
	v_mul_f32_e32 v58, v55, v59
	v_lshlrev_b32_e32 v60, 16, v109
	v_mov_b32_e32 v56, v58
	v_and_b32_e32 v61, 0xffff0000, v109
	v_mul_f32_e32 v55, 0xbfb8aa3b, v60
	v_pk_add_f32 v[50:51], v[50:51], v[168:169] op_sel_hi:[1,0]
	v_mul_f32_e32 v54, 0xbfb8aa3b, v61
	v_pk_mul_f32 v[48:49], v[56:57], v[48:49]
	v_exp_f32_e32 v56, v55
	v_exp_f32_e32 v57, v54
	v_lshlrev_b32_e32 v58, 16, v107
	v_and_b32_e32 v59, 0xffff0000, v107
	v_pk_mul_f32 v[50:51], v[50:51], v[58:59]
	v_pk_add_f32 v[54:55], v[56:57], 1.0 op_sel_hi:[1,0]
	v_cvt_pk_bf16_f32 v48, v48, v49
	v_rcp_f32_e32 v57, v55
	s_nop 0
	v_mul_f32_e32 v55, v61, v57
	v_rcp_f32_e32 v57, v54
	s_nop 0
	v_mul_f32_e32 v56, v60, v57
	v_mov_b32_e32 v54, v56
	v_pk_mul_f32 v[50:51], v[54:55], v[50:51]
	s_nop 0
	v_cvt_pk_bf16_f32 v49, v50, v51
	global_store_dwordx2 v[52:53], v[48:49], off offset:1024
	v_pk_add_f32 v[32:33], v[32:33], v[170:171] op_sel_hi:[1,0]
	s_nop 0
	v_pk_mul_f32 v[32:33], v[32:33], v[42:43]
	v_rcp_f32_e32 v43, v41
	s_nop 0
	v_mul_f32_e32 v41, v44, v43
	v_rcp_f32_e32 v43, v40
	s_nop 0
	v_mul_f32_e32 v42, v39, v43
	v_lshlrev_b32_e32 v44, 16, v105
	v_mov_b32_e32 v40, v42
	v_and_b32_e32 v45, 0xffff0000, v105
	v_mul_f32_e32 v39, 0xbfb8aa3b, v44
	v_pk_add_f32 v[34:35], v[34:35], v[170:171] op_sel_hi:[1,0]
	v_mul_f32_e32 v38, 0xbfb8aa3b, v45
	v_pk_mul_f32 v[32:33], v[40:41], v[32:33]
	v_exp_f32_e32 v40, v39
	v_exp_f32_e32 v41, v38
	v_lshlrev_b32_e32 v42, 16, v101
	v_and_b32_e32 v43, 0xffff0000, v101
	v_pk_mul_f32 v[34:35], v[34:35], v[42:43]
	v_pk_add_f32 v[38:39], v[40:41], 1.0 op_sel_hi:[1,0]
	v_cvt_pk_bf16_f32 v32, v32, v33
	v_rcp_f32_e32 v41, v39
	s_nop 0
	v_mul_f32_e32 v39, v45, v41
	v_rcp_f32_e32 v41, v38
	s_nop 0
	v_mul_f32_e32 v40, v44, v41
	v_mov_b32_e32 v38, v40
	v_pk_mul_f32 v[34:35], v[38:39], v[34:35]
	s_nop 0
	v_cvt_pk_bf16_f32 v33, v34, v35
	global_store_dwordx2 v[36:37], v[32:33], off offset:1024
	v_pk_add_f32 v[0:1], v[0:1], v[172:173] op_sel_hi:[1,0]
	s_nop 0
	v_pk_mul_f32 v[0:1], v[0:1], v[10:11]
	v_rcp_f32_e32 v11, v9
	s_nop 0
	v_mul_f32_e32 v9, v12, v11
	v_rcp_f32_e32 v11, v8
	s_nop 0
	v_mul_f32_e32 v10, v7, v11
	v_lshlrev_b32_e32 v12, 16, v99
	v_mov_b32_e32 v8, v10
	v_and_b32_e32 v13, 0xffff0000, v99
	v_mul_f32_e32 v7, 0xbfb8aa3b, v12
	v_pk_add_f32 v[2:3], v[2:3], v[172:173] op_sel_hi:[1,0]
	v_mul_f32_e32 v6, 0xbfb8aa3b, v13
	v_pk_mul_f32 v[0:1], v[8:9], v[0:1]
	v_exp_f32_e32 v8, v7
	v_exp_f32_e32 v9, v6
	v_lshlrev_b32_e32 v10, 16, v97
	v_and_b32_e32 v11, 0xffff0000, v97
	v_pk_mul_f32 v[2:3], v[2:3], v[10:11]
	v_pk_add_f32 v[6:7], v[8:9], 1.0 op_sel_hi:[1,0]
	v_cvt_pk_bf16_f32 v0, v0, v1
	v_rcp_f32_e32 v9, v7
	s_nop 0
	v_mul_f32_e32 v7, v13, v9
	v_rcp_f32_e32 v9, v6
	s_nop 0
	v_mul_f32_e32 v8, v12, v9
	v_mov_b32_e32 v6, v8
	v_pk_mul_f32 v[2:3], v[6:7], v[2:3]
	s_nop 0
	v_cvt_pk_bf16_f32 v1, v2, v3
	global_store_dwordx2 v[4:5], v[0:1], off offset:1024
	s_barrier
	s_cbranch_scc0 .LBB0_825
	s_branch .LBB0_826
